# attention work queue split into one counter per XCD (workgroup id & 7): each XCD owns 8 (batch, head) pairs so their K/V tiles stream from that XCD's L2
# baseline (speedup 1.0000x reference)
; DI void attn_item(const Params& p, int item, char* smem) {
;     ...
;   if (item < 2048) { bh = item >> 5; const int qb = item & 31; qpos0 = qb * 128; key0 = 0; nkt = LK / 64; orow0 = (bh >> 3) * L + qpos0; }
;   else { const int it = item - 2048; bh = it >> 1; const int qb = it & 1; qpos0 = 4096 + qb * 128; key0 = 4096; nkt = LC / 64; orow0 = NTL + (bh >> 3) * LC + qb * 128; }
; DI void phase_attn(const Params& p, int l, char* smem) {
;     ...
;   for (;;) {
;     __syncthreads();
;     if (tid__ == 0) qslot_sh = (int)__hip_atomic_fetch_add(ctr, 1u, __ATOMIC_RELAXED, __HIP_MEMORY_SCOPE_AGENT);
;     __syncthreads();
;     const int it = qslot_sh;
;     if (it >= nattn) break;
.LBB0_520:
	s_waitcnt lgkmcnt(0)
	s_barrier
	s_and_saveexec_b64 s[4:5], s[0:1]
	s_cbranch_execz .LBB0_522
	v_readlane_b32 s6, v254, 13
	v_readlane_b32 s7, v254, 14
	s_and_b32 s8, s2, 7
	s_lshl_b32 s8, s8, 2
	s_addk_i32 s8, 0x80
	s_add_u32 s6, s6, s8
	s_addc_u32 s7, s7, 0
	s_nop 1
	v_mov_b64_e32 v[2:3], s[6:7]
	flat_atomic_add v0, v[2:3], v233 offset:64 sc0
	s_waitcnt vmcnt(0) lgkmcnt(0)
	ds_write_b32 v234, v0
.LBB0_522:
	s_or_b64 exec, exec, s[4:5]
	s_waitcnt lgkmcnt(0)
	s_barrier
	ds_read_b32 v0, v234
	v_readlane_b32 s4, v254, 12
	s_waitcnt lgkmcnt(0)
	v_readfirstlane_b32 s6, v0
	s_add_i32 s4, s4, 0xfffff800
	s_lshr_b32 s4, s4, 3
	s_addk_i32 s4, 0x100
	s_cmp_ge_i32 s6, s4
	s_mov_b64 s[4:5], -1
	s_cbranch_scc1 .LBB0_519
	s_and_b32 s8, s2, 7
	s_lshl_b32 s9, s8, 8
	s_add_i32 s9, s9, s6
	s_lshl_b32 s8, s8, 4
	s_add_i32 s8, s8, s6
	s_addk_i32 s8, 0x700
	s_cmpk_lt_i32 s6, 0x100
	s_cselect_b32 s6, s9, s8
	v_mov_b32_e32 v2, v163
	s_mov_b32 s4, s2
	s_cmpk_gt_i32 s6, 0x7ff
	s_mov_b64 s[4:5], -1
	s_cbranch_scc0 .LBB0_525
	s_add_i32 s4, s6, 0xfffff800
	s_lshr_b32 s8, s4, 1
	s_lshl_b32 s5, s6, 7
	s_lshl_b32 s4, s4, 4
	s_and_b32 s5, s5, 0x80
	s_and_b32 s4, s4, 0x7fffff00
	s_or_b32 s4, s4, s5
	s_or_b32 s64, s5, 0x1000
	s_add_i32 s9, s4, 0x8000
	s_mov_b64 s[4:5], 0
